# attention cumsum prologue: 32 single-dword sc1 loads per lane -> 8 dwordx4 sc1 loads
# speedup vs baseline: 1.0033x; 1.0033x over previous
; __device__ __forceinline__ int hw_lane() { int l = (int)__builtin_amdgcn_mbcnt_hi(~0u, __builtin_amdgcn_mbcnt_lo(~0u, 0u)); asm volatile("" : "+v"(l)); return l; }
;     ...
;       if(wv==0){ const int lane=hw_lane(); const float* p=T.LS+(long)u.bh*SEQ+32*lane; float v[32]; float run=0.f;
;         _Pragma("unroll") for(int j=0;j<32;++j){ v[j]=__hip_atomic_load(p+j,__ATOMIC_RELAXED,__HIP_MEMORY_SCOPE_AGENT); }
;         _Pragma("unroll") for(int j=0;j<32;++j){ run+=v[j]; v[j]=run; }
;         float incl=run;
;         _Pragma("unroll") for(int o=1;o<64;o<<=1){ const float t=__shfl_up(incl,o); if(lane>=o)incl+=t; }
;         const float excl=incl-run;
;         __attribute__((address_space(3))) float* cl=(__attribute__((address_space(3))) float*)((__attribute__((address_space(3))) char*)lds+LDS_CL)+32*lane;
;         _Pragma("unroll") for(int j=0;j<32;++j) cl[j]=v[j]+excl; }
;       asm volatile("s_waitcnt lgkmcnt(0)\n\ts_barrier":::"memory"); }
.LBB0_388:
	s_cmp_eq_u32 s40, s41
	s_cbranch_scc1 .LBB0_392
	s_and_b64 vcc, exec, s[4:5]
	s_cbranch_vccnz .LBB0_391
	s_ashr_i32 s41, s40, 31
	v_mov_b32_e32 v0, v212
	s_lshl_b64 s[8:9], s[40:41], 13
	s_add_u32 s8, s60, s8
	v_lshlrev_b32_e32 v2, 5, v0
	s_addc_u32 s9, s63, s9
	v_ashrrev_i32_e32 v3, 31, v2
	v_lshl_add_u64 v[2:3], v[2:3], 2, s[8:9]
	global_load_dwordx4 v[4:7], v[2:3], off sc1
	global_load_dwordx4 v[8:11], v[2:3], off offset:16 sc1
	global_load_dwordx4 v[12:15], v[2:3], off offset:32 sc1
	global_load_dwordx4 v[16:19], v[2:3], off offset:48 sc1
	global_load_dwordx4 v[20:23], v[2:3], off offset:64 sc1
	global_load_dwordx4 v[24:27], v[2:3], off offset:80 sc1
	global_load_dwordx4 v[28:31], v[2:3], off offset:96 sc1
	global_load_dwordx4 v[32:35], v[2:3], off offset:112 sc1
	v_cmp_gt_i32_e32 vcc, 1, v0
	v_lshl_add_u32 v36, v0, 7, 0
	v_add_u32_e32 v36, 0x16800, v36
	s_waitcnt vmcnt(7)
	v_add_f32_e32 v2, 0, v4
	s_waitcnt vmcnt(7)
	v_add_f32_e32 v3, v2, v5
	s_waitcnt vmcnt(7)
	v_add_f32_e32 v4, v3, v6
	s_waitcnt vmcnt(7)
	v_add_f32_e32 v5, v4, v7
	s_waitcnt vmcnt(6)
	v_add_f32_e32 v6, v5, v8
	s_waitcnt vmcnt(6)
	v_add_f32_e32 v7, v6, v9
	s_waitcnt vmcnt(6)
	v_add_f32_e32 v8, v7, v10
	s_waitcnt vmcnt(6)
	v_add_f32_e32 v9, v8, v11
	s_waitcnt vmcnt(5)
	v_add_f32_e32 v10, v9, v12
	s_waitcnt vmcnt(5)
	v_add_f32_e32 v11, v10, v13
	s_waitcnt vmcnt(5)
	v_add_f32_e32 v12, v11, v14
	s_waitcnt vmcnt(5)
	v_add_f32_e32 v13, v12, v15
	s_waitcnt vmcnt(4)
	v_add_f32_e32 v14, v13, v16
	s_waitcnt vmcnt(4)
	v_add_f32_e32 v15, v14, v17
	s_waitcnt vmcnt(4)
	v_add_f32_e32 v16, v15, v18
	s_waitcnt vmcnt(4)
	v_add_f32_e32 v17, v16, v19
	s_waitcnt vmcnt(3)
	v_add_f32_e32 v18, v17, v20
	s_waitcnt vmcnt(3)
	v_add_f32_e32 v19, v18, v21
	s_waitcnt vmcnt(3)
	v_add_f32_e32 v20, v19, v22
	s_waitcnt vmcnt(3)
	v_add_f32_e32 v21, v20, v23
	s_waitcnt vmcnt(2)
	v_add_f32_e32 v22, v21, v24
	s_waitcnt vmcnt(2)
	v_add_f32_e32 v23, v22, v25
	s_waitcnt vmcnt(2)
	v_add_f32_e32 v24, v23, v26
	s_waitcnt vmcnt(2)
	v_add_f32_e32 v25, v24, v27
	s_waitcnt vmcnt(1)
	v_add_f32_e32 v26, v25, v28
	s_waitcnt vmcnt(1)
	v_add_f32_e32 v27, v26, v29
	s_waitcnt vmcnt(1)
	v_add_f32_e32 v28, v27, v30
	s_waitcnt vmcnt(1)
	v_add_f32_e32 v29, v28, v31
	s_waitcnt vmcnt(0)
	v_add_f32_e32 v30, v29, v32
	s_waitcnt vmcnt(0)
	v_add_f32_e32 v31, v30, v33
	s_waitcnt vmcnt(0)
	v_add_f32_e32 v32, v31, v34
	s_waitcnt vmcnt(0)
	v_add_f32_e32 v33, v32, v35
	ds_bpermute_b32 v34, v221, v33
	s_waitcnt lgkmcnt(0)
	v_add_f32_e32 v34, v33, v34
	v_cndmask_b32_e32 v34, v34, v33, vcc
	ds_bpermute_b32 v35, v222, v34
	v_cmp_gt_i32_e32 vcc, 2, v0
	s_waitcnt lgkmcnt(0)
	v_add_f32_e32 v35, v34, v35
	v_cndmask_b32_e32 v34, v35, v34, vcc
	ds_bpermute_b32 v35, v223, v34
	v_cmp_gt_i32_e32 vcc, 4, v0
	s_waitcnt lgkmcnt(0)
	v_add_f32_e32 v35, v34, v35
	v_cndmask_b32_e32 v34, v35, v34, vcc
	ds_bpermute_b32 v35, v224, v34
	v_cmp_gt_i32_e32 vcc, 8, v0
	s_waitcnt lgkmcnt(0)
	v_add_f32_e32 v35, v34, v35
	v_cndmask_b32_e32 v34, v35, v34, vcc
	ds_bpermute_b32 v35, v225, v34
	v_cmp_gt_i32_e32 vcc, 16, v0
	s_waitcnt lgkmcnt(0)
	v_add_f32_e32 v35, v34, v35
	v_cndmask_b32_e32 v34, v35, v34, vcc
	ds_bpermute_b32 v35, v226, v34
	v_cmp_gt_i32_e32 vcc, 32, v0
	s_waitcnt lgkmcnt(0)
	v_add_f32_e32 v35, v34, v35
	v_cndmask_b32_e32 v0, v35, v34, vcc
	v_sub_f32_e32 v0, v0, v33
	v_pk_add_f32 v[2:3], v[2:3], v[0:1] op_sel_hi:[1,0]
	v_pk_add_f32 v[4:5], v[4:5], v[0:1] op_sel_hi:[1,0]
	v_pk_add_f32 v[6:7], v[6:7], v[0:1] op_sel_hi:[1,0]
	v_pk_add_f32 v[8:9], v[8:9], v[0:1] op_sel_hi:[1,0]
	v_pk_add_f32 v[10:11], v[10:11], v[0:1] op_sel_hi:[1,0]
	v_pk_add_f32 v[12:13], v[12:13], v[0:1] op_sel_hi:[1,0]
	v_pk_add_f32 v[14:15], v[14:15], v[0:1] op_sel_hi:[1,0]
	v_pk_add_f32 v[16:17], v[16:17], v[0:1] op_sel_hi:[1,0]
	v_pk_add_f32 v[18:19], v[18:19], v[0:1] op_sel_hi:[1,0]
	v_pk_add_f32 v[20:21], v[20:21], v[0:1] op_sel_hi:[1,0]
	v_pk_add_f32 v[22:23], v[22:23], v[0:1] op_sel_hi:[1,0]
	v_pk_add_f32 v[24:25], v[24:25], v[0:1] op_sel_hi:[1,0]
	v_pk_add_f32 v[26:27], v[26:27], v[0:1] op_sel_hi:[1,0]
	v_pk_add_f32 v[28:29], v[28:29], v[0:1] op_sel_hi:[1,0]
	v_pk_add_f32 v[30:31], v[30:31], v[0:1] op_sel_hi:[1,0]
	v_pk_add_f32 v[32:33], v[32:33], v[0:1] op_sel_hi:[1,0]
	ds_write_b128 v36, v[2:5]
	ds_write_b128 v36, v[6:9] offset:16
	ds_write_b128 v36, v[10:13] offset:32
	ds_write_b128 v36, v[14:17] offset:48
	ds_write_b128 v36, v[18:21] offset:64
	ds_write_b128 v36, v[22:25] offset:80
	ds_write_b128 v36, v[26:29] offset:96
	ds_write_b128 v36, v[30:33] offset:112
